# st8: rwkv_post first As staging load issued ahead of the workgroup barrier (on top of st7)
# baseline (speedup 1.0000x reference)
; #define LAS __attribute__((address_space(3)))
; DI void rwkv_post_tile(int j, int item, LAS unsigned char* lds) {
;     ...
;     const int m0 = tile * 128;
;     __syncthreads();
;     for (int i = 0; i < 6; ++i) { const int idx = tid + 512 * i; const int row = idx / 24, ch = idx - row * 24;
;         *(LAS u32x4*)(As + row * 200 + ch * 8) = *(const u32x4*)(G1 + (size_t)(m0 + row) * 256 + ch * 8); }
;     const size_t m = (size_t)m0 + wave * 16 + fr;
.LBB0_98:
	s_andn2_b64 vcc, exec, s[2:3]
	s_cbranch_vccnz .LBB0_95
	v_readlane_b32 s14, v255, 17
	v_readlane_b32 s15, v255, 18
	s_mov_b64 s[4:5], s[14:15]
	s_waitcnt lgkmcnt(0)
	s_load_dwordx2 s[12:13], s[4:5], 0x118
	s_bfe_u32 s3, s18, 0x20001
	s_and_b32 s24, s20, 0xffffff80
	s_lshl_b32 s2, s3, 8
	s_ashr_i32 s25, s24, 31
	v_mov_b32_e32 v0, v182
	s_mov_b32 s26, 0x2aaaaaab
	s_waitcnt lgkmcnt(0)
	s_add_u32 s16, s12, 0x1d500000
	s_waitcnt vmcnt(0)
	v_mul_hi_i32 v2, v0, s26
	s_addc_u32 s17, s13, 0
	s_lshl_b32 s29, s23, 5
	v_lshrrev_b32_e32 v3, 31, v2
	v_ashrrev_i32_e32 v2, 2, v2
	s_and_b32 s29, s29, 0xffffff80
	v_add_u32_e32 v20, v2, v3
	v_add_u32_e32 v2, s29, v20
	s_movk_i32 s27, 0xffe8
	v_ashrrev_i32_e32 v3, 31, v2
	v_mad_u64_u32 v[8:9], s[34:35], v20, s27, v[0:1]
	v_lshlrev_b64 v[2:3], 9, v[2:3]
	v_lshl_add_u64 v[4:5], s[16:17], 0, v[2:3]
	v_lshlrev_b32_e32 v2, 3, v8
	s_mov_b64 s[4:5], s[14:15]
	v_ashrrev_i32_e32 v3, 31, v2
	v_lshlrev_b64 v[2:3], 1, v[2:3]
	s_load_dwordx2 s[4:5], s[4:5], 0xf8
	v_lshl_add_u64 v[4:5], v[4:5], 0, v[2:3]
	s_load_dwordx2 s[14:15], s[14:15], 0x100
	s_waitcnt vmcnt(0) lgkmcnt(0)
	global_load_dwordx4 v[240:243], v[4:5], off
	s_barrier
	s_movk_i32 s36, 0x190
	v_mul_lo_u32 v9, v20, s36
	v_lshl_add_u32 v21, v8, 4, v9
	v_readfirstlane_b32 s28, v0
	v_add_u32_e32 v167, 0xc810, v21
	v_add_u32_e32 v4, 0x200, v0
	v_mul_hi_i32 v5, v4, s26
	v_lshrrev_b32_e32 v6, 31, v5
	v_ashrrev_i32_e32 v5, 2, v5
	v_add_u32_e32 v22, v5, v6
	v_mad_u64_u32 v[10:11], s[34:35], v22, s27, v[4:5]
	v_add_u32_e32 v4, s29, v22
	v_ashrrev_i32_e32 v5, 31, v4
	v_lshlrev_b64 v[4:5], 9, v[4:5]
	v_lshl_add_u64 v[6:7], s[16:17], 0, v[4:5]
	v_lshlrev_b32_e32 v4, 3, v10
	v_ashrrev_i32_e32 v5, 31, v4
	v_lshlrev_b64 v[4:5], 1, v[4:5]
	v_lshl_add_u64 v[6:7], v[6:7], 0, v[4:5]
	global_load_dwordx4 v[218:221], v[6:7], off
	v_mul_lo_u32 v11, v22, s36
	v_lshl_add_u32 v23, v10, 4, v11
	v_add_u32_e32 v168, 0xc810, v23
	v_add_u32_e32 v6, 0x400, v0
	v_mul_hi_i32 v7, v6, s26
	v_lshrrev_b32_e32 v8, 31, v7
	v_ashrrev_i32_e32 v7, 2, v7
	v_add_u32_e32 v24, v7, v8
	v_mad_u64_u32 v[10:11], s[34:35], v24, s27, v[6:7]
	v_add_u32_e32 v6, s29, v24
	v_ashrrev_i32_e32 v7, 31, v6
	v_lshlrev_b32_e32 v8, 3, v10
	v_lshlrev_b64 v[6:7], 9, v[6:7]
	v_ashrrev_i32_e32 v9, 31, v8
	v_lshl_add_u64 v[6:7], s[16:17], 0, v[6:7]
	v_lshlrev_b64 v[12:13], 1, v[8:9]
	v_lshl_add_u64 v[6:7], v[6:7], 0, v[12:13]
	global_load_dwordx4 v[222:225], v[6:7], off
	v_mul_lo_u32 v11, v24, s36
	v_lshl_add_u32 v25, v10, 4, v11
	v_add_u32_e32 v169, 0xc810, v25
	v_add_u32_e32 v6, 0x600, v0
	v_mul_hi_i32 v7, v6, s26
	v_lshrrev_b32_e32 v8, 31, v7
	v_ashrrev_i32_e32 v7, 2, v7
	v_add_u32_e32 v26, v7, v8
	v_mad_u64_u32 v[10:11], s[34:35], v26, s27, v[6:7]
	v_add_u32_e32 v6, s29, v26
	v_ashrrev_i32_e32 v7, 31, v6
	v_lshlrev_b32_e32 v8, 3, v10
	v_lshlrev_b64 v[6:7], 9, v[6:7]
	v_ashrrev_i32_e32 v9, 31, v8
	v_lshl_add_u64 v[6:7], s[16:17], 0, v[6:7]
	v_lshlrev_b64 v[14:15], 1, v[8:9]
	v_lshl_add_u64 v[6:7], v[6:7], 0, v[14:15]
	global_load_dwordx4 v[226:229], v[6:7], off
	v_mul_lo_u32 v11, v26, s36
	v_lshl_add_u32 v27, v10, 4, v11
	v_add_u32_e32 v170, 0xc810, v27
	v_add_u32_e32 v6, 0x800, v0
	v_mul_hi_i32 v7, v6, s26
	v_lshrrev_b32_e32 v8, 31, v7
	v_ashrrev_i32_e32 v7, 2, v7
	v_add_u32_e32 v28, v7, v8
	v_mad_u64_u32 v[10:11], s[34:35], v28, s27, v[6:7]
	v_add_u32_e32 v6, s29, v28
	v_ashrrev_i32_e32 v7, 31, v6
	v_lshlrev_b32_e32 v8, 3, v10
	v_lshlrev_b64 v[6:7], 9, v[6:7]
	v_ashrrev_i32_e32 v9, 31, v8
	v_lshl_add_u64 v[6:7], s[16:17], 0, v[6:7]
	v_lshlrev_b64 v[16:17], 1, v[8:9]
	v_lshl_add_u64 v[6:7], v[6:7], 0, v[16:17]
	global_load_dwordx4 v[230:233], v[6:7], off
	v_mul_lo_u32 v11, v28, s36
	v_lshl_add_u32 v29, v10, 4, v11
	v_add_u32_e32 v171, 0xc810, v29
	v_add_u32_e32 v6, 0xa00, v0
	v_mul_hi_i32 v7, v6, s26
	v_lshrrev_b32_e32 v8, 31, v7
	v_ashrrev_i32_e32 v7, 2, v7
	v_add_u32_e32 v30, v7, v8
	v_mad_u64_u32 v[10:11], s[34:35], v30, s27, v[6:7]
	v_add_u32_e32 v6, s29, v30
	v_ashrrev_i32_e32 v7, 31, v6
	v_lshlrev_b32_e32 v8, 3, v10
	v_lshlrev_b64 v[6:7], 9, v[6:7]
	v_ashrrev_i32_e32 v9, 31, v8
	v_lshl_add_u64 v[6:7], s[16:17], 0, v[6:7]
	v_lshlrev_b64 v[18:19], 1, v[8:9]
	v_lshl_add_u64 v[6:7], v[6:7], 0, v[18:19]
	global_load_dwordx4 v[236:239], v[6:7], off
	s_ashr_i32 s16, s28, 2
	v_mul_lo_u32 v11, v30, s36
	s_and_b32 s28, s16, -16
	v_lshl_add_u32 v10, v10, 4, v11
	s_mul_i32 s16, s28, 0x190
	v_and_b32_e32 v11, 15, v0
	v_bfe_u32 v0, v0, 4, 2
	s_movk_i32 s26, 0x180
	s_ashr_i32 s29, s28, 31
	v_mul_u32_u24_e32 v31, 0x190, v11
	v_add_u32_e32 v172, 0xc810, v10
	s_waitcnt vmcnt(0)
	ds_write_b128 v21, v[240:243] offset:16
	ds_write_b128 v23, v[218:221] offset:16
	ds_write_b128 v25, v[222:225] offset:16
	ds_write_b128 v27, v[226:229] offset:16
	ds_write_b128 v29, v[230:233] offset:16
	ds_write_b128 v10, v[236:239] offset:16
	v_mov_b32_e32 v6, s16
	v_mad_u32_u24 v6, v11, s36, v6
	v_lshlrev_b32_e32 v7, 4, v0
	v_add3_u32 v139, v6, v7, 16
	v_add_u32_e32 v32, 0xc810, v7
	v_and_b32_e32 v7, 64, v187
	v_xor_b32_e32 v6, 16, v187
	v_add_u32_e32 v7, 64, v7
	v_cmp_lt_i32_e32 vcc, v6, v7
	v_add_u32_e32 v8, s2, v20
	v_lshl_or_b32 v0, v0, 2, s2
	v_cndmask_b32_e32 v6, v187, v6, vcc
	v_lshlrev_b32_e32 v165, 2, v6
	v_xor_b32_e32 v6, 32, v187
	v_cmp_lt_i32_e32 vcc, v6, v7
	v_add_u32_e32 v173, v32, v31
	s_nop 0
	v_cndmask_b32_e32 v6, v187, v6, vcc
	v_lshlrev_b32_e32 v166, 2, v6
	v_mov_b64_e32 v[6:7], s[80:81]
	v_mad_i64_i32 v[8:9], s[16:17], v8, s26, v[6:7]
	s_add_u32 s16, s24, s28
	s_addc_u32 s17, s25, s29
	v_lshl_add_u64 v[70:71], v[8:9], 0, v[2:3]
	v_or_b32_e32 v2, s16, v11
	v_mov_b32_e32 v3, s17
	v_add_u32_e32 v8, s2, v22
	v_lshlrev_b64 v[72:73], 6, v[2:3]
	v_mad_i64_i32 v[8:9], s[16:17], v8, s26, v[6:7]
	v_lshlrev_b64 v[80:81], 11, v[2:3]
	v_add_u32_e32 v2, s2, v28
	v_lshl_add_u64 v[74:75], v[8:9], 0, v[4:5]
	v_add_u32_e32 v4, s2, v24
	v_mad_i64_i32 v[2:3], s[16:17], v2, s26, v[6:7]
	v_mad_i64_i32 v[4:5], s[16:17], v4, s26, v[6:7]
	v_lshl_add_u64 v[82:83], v[2:3], 0, v[16:17]
	v_add_u32_e32 v2, s2, v30
	v_lshl_or_b32 v72, s3, 4, v72
	v_lshl_add_u64 v[76:77], v[4:5], 0, v[12:13]
	v_add_u32_e32 v4, s2, v26
	v_mad_i64_i32 v[2:3], s[2:3], v2, s26, v[6:7]
	s_add_u32 s2, s14, s22
	v_lshl_or_b32 v80, v0, 1, v80
	s_addc_u32 s3, s15, 0
	v_lshlrev_b32_e32 v0, 2, v0
	v_lshl_add_u64 v[86:87], s[2:3], 0, v[0:1]
	s_add_u32 s2, s4, s22
	v_mad_i64_i32 v[4:5], s[16:17], v4, s26, v[6:7]
	s_addc_u32 s3, s5, 0
	v_lshl_add_u64 v[78:79], v[4:5], 0, v[14:15]
	v_lshl_add_u64 v[84:85], v[2:3], 0, v[18:19]
	v_lshl_add_u64 v[88:89], s[2:3], 0, v[0:1]
	s_mov_b64 s[14:15], 0
	s_mov_b32 s3, 0x800000
	s_mov_b64 s[16:17], 0x100
	s_mov_b64 s[24:25], 0xc000
